# in-projection Z stores write-through (sc1)
# baseline (speedup 1.0000x reference)
.LBB0_239:
	s_and_b64 s[28:29], exec, s[28:29]
	s_mov_b32 s3, 0x3600000
	s_cselect_b32 s3, s3, 0x4800000
	s_and_b64 s[8:9], s[8:9], exec
	s_cselect_b32 s3, 0x1200000, s3
	s_lshl_b32 s3, s3, 1
	s_add_u32 s8, s58, s3
	s_addc_u32 s9, s59, 0
	s_lshl_b32 s3, s92, 8
	s_and_b32 s3, s3, 0x700
	v_or_b32_e32 v130, s3, v166
	v_lshlrev_b32_e32 v130, 1, v130
	v_ashrrev_i32_e32 v137, 31, v136
	v_lshl_add_u64 v[142:143], s[8:9], 0, v[130:131]
	v_lshlrev_b64 v[144:145], 12, v[136:137]
	v_cndmask_b32_e64 v130, 0, 1, s[10:11]
	v_lshl_add_u64 v[144:145], v[142:143], 0, v[144:145]
	v_cmp_ne_u32_e64 s[8:9], 1, v130
	s_andn2_b64 vcc, exec, s[10:11]
	v_cvt_pk_bf16_f32 v172, v148, v149
	v_cvt_pk_bf16_f32 v173, v146, v147
	v_cvt_pk_bf16_f32 v174, v152, v153
	v_cvt_pk_bf16_f32 v175, v150, v151
	global_store_dwordx4 v[144:145], v[172:175], off sc1
	s_cbranch_vccnz .LBB0_241
	v_pk_mul_f32 v[146:147], v[122:123], v[122:123]
	v_pk_mul_f32 v[148:149], v[120:121], v[120:121]
	v_pk_mul_f32 v[150:151], v[114:115], v[114:115]
	v_pk_mul_f32 v[152:153], v[112:113], v[112:113]
	v_pk_fma_f32 v[148:149], v[140:141], v[148:149], v[138:139]
	v_pk_fma_f32 v[146:147], v[140:141], v[146:147], v[138:139]
	v_pk_fma_f32 v[152:153], v[140:141], v[152:153], v[138:139]
	v_pk_fma_f32 v[150:151], v[140:141], v[150:151], v[138:139]
	v_pk_mul_f32 v[148:149], v[120:121], v[148:149]
	v_pk_mul_f32 v[146:147], v[122:123], v[146:147]
	v_pk_mul_f32 v[152:153], v[112:113], v[152:153]
	v_pk_mul_f32 v[150:151], v[114:115], v[150:151]
	v_exp_f32_e32 v148, v148
	v_exp_f32_e32 v149, v149
	v_exp_f32_e32 v146, v146
	v_exp_f32_e32 v147, v147
	v_exp_f32_e32 v152, v152
	v_exp_f32_e32 v153, v153
	v_exp_f32_e32 v150, v150
	v_exp_f32_e32 v151, v151
	v_pk_add_f32 v[148:149], v[148:149], 1.0 op_sel_hi:[1,0]
	v_pk_add_f32 v[146:147], v[146:147], 1.0 op_sel_hi:[1,0]
	v_pk_add_f32 v[152:153], v[152:153], 1.0 op_sel_hi:[1,0]
	v_pk_add_f32 v[150:151], v[150:151], 1.0 op_sel_hi:[1,0]
	v_rcp_f32_e32 v148, v148
	v_rcp_f32_e32 v149, v149
	v_rcp_f32_e32 v146, v146
	v_rcp_f32_e32 v147, v147
	v_rcp_f32_e32 v152, v152
	v_rcp_f32_e32 v153, v153
	v_rcp_f32_e32 v150, v150
	v_rcp_f32_e32 v151, v151
	v_pk_mul_f32 v[146:147], v[122:123], v[146:147]
	v_pk_mul_f32 v[148:149], v[120:121], v[148:149]
	v_pk_mul_f32 v[152:153], v[112:113], v[152:153]
	v_pk_mul_f32 v[150:151], v[114:115], v[150:151]
	s_branch .LBB0_242

.LBB0_242:
	s_and_b64 vcc, exec, s[8:9]
	v_cvt_pk_bf16_f32 v172, v148, v149
	v_cvt_pk_bf16_f32 v173, v146, v147
	v_cvt_pk_bf16_f32 v174, v152, v153
	v_cvt_pk_bf16_f32 v175, v150, v151
	global_store_dwordx4 v[144:145], v[172:175], off offset:256 sc1
	s_cbranch_vccnz .LBB0_244
	v_pk_mul_f32 v[146:147], v[108:109], v[108:109]
	v_pk_mul_f32 v[144:145], v[110:111], v[110:111]
	v_pk_fma_f32 v[146:147], v[140:141], v[146:147], v[138:139]
	v_pk_mul_f32 v[150:151], v[100:101], v[100:101]
	v_pk_mul_f32 v[146:147], v[108:109], v[146:147]
	v_pk_fma_f32 v[144:145], v[140:141], v[144:145], v[138:139]
	v_exp_f32_e32 v146, v146
	v_exp_f32_e32 v147, v147
	v_pk_fma_f32 v[150:151], v[140:141], v[150:151], v[138:139]
	v_pk_mul_f32 v[144:145], v[110:111], v[144:145]
	v_pk_mul_f32 v[150:151], v[100:101], v[150:151]
	v_pk_add_f32 v[146:147], v[146:147], 1.0 op_sel_hi:[1,0]
	v_exp_f32_e32 v144, v144
	v_rcp_f32_e32 v148, v146
	v_rcp_f32_e32 v149, v147
	v_pk_mul_f32 v[146:147], v[102:103], v[102:103]
	v_exp_f32_e32 v145, v145
	v_pk_fma_f32 v[146:147], v[140:141], v[146:147], v[138:139]
	v_exp_f32_e32 v150, v150
	v_pk_mul_f32 v[146:147], v[102:103], v[146:147]
	v_exp_f32_e32 v151, v151
	v_exp_f32_e32 v146, v146
	v_exp_f32_e32 v147, v147
	v_pk_add_f32 v[144:145], v[144:145], 1.0 op_sel_hi:[1,0]
	v_pk_add_f32 v[150:151], v[150:151], 1.0 op_sel_hi:[1,0]
	v_rcp_f32_e32 v144, v144
	v_pk_add_f32 v[146:147], v[146:147], 1.0 op_sel_hi:[1,0]
	v_rcp_f32_e32 v145, v145
	v_rcp_f32_e32 v152, v150
	v_rcp_f32_e32 v153, v151
	v_rcp_f32_e32 v150, v146
	v_rcp_f32_e32 v151, v147
	v_pk_mul_f32 v[146:147], v[110:111], v[144:145]
	v_pk_mul_f32 v[148:149], v[108:109], v[148:149]
	v_pk_mul_f32 v[152:153], v[100:101], v[152:153]
	v_pk_mul_f32 v[150:151], v[102:103], v[150:151]
	s_branch .LBB0_245

.LBB0_245:
	v_or_b32_e32 v144, 16, v136
	v_ashrrev_i32_e32 v145, 31, v144
	v_lshlrev_b64 v[144:145], 12, v[144:145]
	v_lshl_add_u64 v[144:145], v[142:143], 0, v[144:145]
	s_and_b64 vcc, exec, s[8:9]
	v_cvt_pk_bf16_f32 v172, v148, v149
	v_cvt_pk_bf16_f32 v173, v146, v147
	v_cvt_pk_bf16_f32 v174, v152, v153
	v_cvt_pk_bf16_f32 v175, v150, v151
	global_store_dwordx4 v[144:145], v[172:175], off sc1
	s_cbranch_vccnz .LBB0_247
	v_pk_mul_f32 v[146:147], v[106:107], v[106:107]
	v_pk_mul_f32 v[148:149], v[104:105], v[104:105]
	v_pk_mul_f32 v[150:151], v[98:99], v[98:99]
	v_pk_mul_f32 v[152:153], v[96:97], v[96:97]
	v_pk_fma_f32 v[148:149], v[140:141], v[148:149], v[138:139]
	v_pk_fma_f32 v[146:147], v[140:141], v[146:147], v[138:139]
	v_pk_fma_f32 v[152:153], v[140:141], v[152:153], v[138:139]
	v_pk_fma_f32 v[150:151], v[140:141], v[150:151], v[138:139]
	v_pk_mul_f32 v[148:149], v[104:105], v[148:149]
	v_pk_mul_f32 v[146:147], v[106:107], v[146:147]
	v_pk_mul_f32 v[152:153], v[96:97], v[152:153]
	v_pk_mul_f32 v[150:151], v[98:99], v[150:151]
	v_exp_f32_e32 v148, v148
	v_exp_f32_e32 v149, v149
	v_exp_f32_e32 v146, v146
	v_exp_f32_e32 v147, v147
	v_exp_f32_e32 v152, v152
	v_exp_f32_e32 v153, v153
	v_exp_f32_e32 v150, v150
	v_exp_f32_e32 v151, v151
	v_pk_add_f32 v[148:149], v[148:149], 1.0 op_sel_hi:[1,0]
	v_pk_add_f32 v[146:147], v[146:147], 1.0 op_sel_hi:[1,0]
	v_pk_add_f32 v[152:153], v[152:153], 1.0 op_sel_hi:[1,0]
	v_pk_add_f32 v[150:151], v[150:151], 1.0 op_sel_hi:[1,0]
	v_rcp_f32_e32 v148, v148
	v_rcp_f32_e32 v149, v149
	v_rcp_f32_e32 v146, v146
	v_rcp_f32_e32 v147, v147
	v_rcp_f32_e32 v152, v152
	v_rcp_f32_e32 v153, v153
	v_rcp_f32_e32 v150, v150
	v_rcp_f32_e32 v151, v151
	v_pk_mul_f32 v[146:147], v[106:107], v[146:147]
	v_pk_mul_f32 v[148:149], v[104:105], v[148:149]
	v_pk_mul_f32 v[152:153], v[96:97], v[152:153]
	v_pk_mul_f32 v[150:151], v[98:99], v[150:151]
	s_branch .LBB0_248

.LBB0_248:
	s_and_b64 vcc, exec, s[8:9]
	v_cvt_pk_bf16_f32 v172, v148, v149
	v_cvt_pk_bf16_f32 v173, v146, v147
	v_cvt_pk_bf16_f32 v174, v152, v153
	v_cvt_pk_bf16_f32 v175, v150, v151
	global_store_dwordx4 v[144:145], v[172:175], off offset:256 sc1
	s_cbranch_vccnz .LBB0_250
	v_pk_mul_f32 v[146:147], v[92:93], v[92:93]
	v_pk_mul_f32 v[144:145], v[94:95], v[94:95]
	v_pk_fma_f32 v[146:147], v[140:141], v[146:147], v[138:139]
	v_pk_mul_f32 v[150:151], v[84:85], v[84:85]
	v_pk_mul_f32 v[146:147], v[92:93], v[146:147]
	v_pk_fma_f32 v[144:145], v[140:141], v[144:145], v[138:139]
	v_exp_f32_e32 v146, v146
	v_exp_f32_e32 v147, v147
	v_pk_fma_f32 v[150:151], v[140:141], v[150:151], v[138:139]
	v_pk_mul_f32 v[144:145], v[94:95], v[144:145]
	v_pk_mul_f32 v[150:151], v[84:85], v[150:151]
	v_pk_add_f32 v[146:147], v[146:147], 1.0 op_sel_hi:[1,0]
	v_exp_f32_e32 v144, v144
	v_rcp_f32_e32 v148, v146
	v_rcp_f32_e32 v149, v147
	v_pk_mul_f32 v[146:147], v[86:87], v[86:87]
	v_exp_f32_e32 v145, v145
	v_pk_fma_f32 v[146:147], v[140:141], v[146:147], v[138:139]
	v_exp_f32_e32 v150, v150
	v_pk_mul_f32 v[146:147], v[86:87], v[146:147]
	v_exp_f32_e32 v151, v151
	v_exp_f32_e32 v146, v146
	v_exp_f32_e32 v147, v147
	v_pk_add_f32 v[144:145], v[144:145], 1.0 op_sel_hi:[1,0]
	v_pk_add_f32 v[150:151], v[150:151], 1.0 op_sel_hi:[1,0]
	v_rcp_f32_e32 v144, v144
	v_pk_add_f32 v[146:147], v[146:147], 1.0 op_sel_hi:[1,0]
	v_rcp_f32_e32 v145, v145
	v_rcp_f32_e32 v152, v150
	v_rcp_f32_e32 v153, v151
	v_rcp_f32_e32 v150, v146
	v_rcp_f32_e32 v151, v147
	v_pk_mul_f32 v[146:147], v[94:95], v[144:145]
	v_pk_mul_f32 v[148:149], v[92:93], v[148:149]
	v_pk_mul_f32 v[152:153], v[84:85], v[152:153]
	v_pk_mul_f32 v[150:151], v[86:87], v[150:151]
	s_branch .LBB0_251

.LBB0_251:
	v_or_b32_e32 v144, 32, v136
	v_ashrrev_i32_e32 v145, 31, v144
	v_lshlrev_b64 v[144:145], 12, v[144:145]
	v_lshl_add_u64 v[144:145], v[142:143], 0, v[144:145]
	s_and_b64 vcc, exec, s[8:9]
	v_cvt_pk_bf16_f32 v172, v148, v149
	v_cvt_pk_bf16_f32 v173, v146, v147
	v_cvt_pk_bf16_f32 v174, v152, v153
	v_cvt_pk_bf16_f32 v175, v150, v151
	global_store_dwordx4 v[144:145], v[172:175], off sc1
	s_cbranch_vccnz .LBB0_253
	v_pk_mul_f32 v[146:147], v[90:91], v[90:91]
	v_pk_mul_f32 v[148:149], v[88:89], v[88:89]
	v_pk_mul_f32 v[150:151], v[82:83], v[82:83]
	v_pk_mul_f32 v[152:153], v[80:81], v[80:81]
	v_pk_fma_f32 v[148:149], v[140:141], v[148:149], v[138:139]
	v_pk_fma_f32 v[146:147], v[140:141], v[146:147], v[138:139]
	v_pk_fma_f32 v[152:153], v[140:141], v[152:153], v[138:139]
	v_pk_fma_f32 v[150:151], v[140:141], v[150:151], v[138:139]
	v_pk_mul_f32 v[148:149], v[88:89], v[148:149]
	v_pk_mul_f32 v[146:147], v[90:91], v[146:147]
	v_pk_mul_f32 v[152:153], v[80:81], v[152:153]
	v_pk_mul_f32 v[150:151], v[82:83], v[150:151]
	v_exp_f32_e32 v148, v148
	v_exp_f32_e32 v149, v149
	v_exp_f32_e32 v146, v146
	v_exp_f32_e32 v147, v147
	v_exp_f32_e32 v152, v152
	v_exp_f32_e32 v153, v153
	v_exp_f32_e32 v150, v150
	v_exp_f32_e32 v151, v151
	v_pk_add_f32 v[148:149], v[148:149], 1.0 op_sel_hi:[1,0]
	v_pk_add_f32 v[146:147], v[146:147], 1.0 op_sel_hi:[1,0]
	v_pk_add_f32 v[152:153], v[152:153], 1.0 op_sel_hi:[1,0]
	v_pk_add_f32 v[150:151], v[150:151], 1.0 op_sel_hi:[1,0]
	v_rcp_f32_e32 v148, v148
	v_rcp_f32_e32 v149, v149
	v_rcp_f32_e32 v146, v146
	v_rcp_f32_e32 v147, v147
	v_rcp_f32_e32 v152, v152
	v_rcp_f32_e32 v153, v153
	v_rcp_f32_e32 v150, v150
	v_rcp_f32_e32 v151, v151
	v_pk_mul_f32 v[146:147], v[90:91], v[146:147]
	v_pk_mul_f32 v[148:149], v[88:89], v[148:149]
	v_pk_mul_f32 v[152:153], v[80:81], v[152:153]
	v_pk_mul_f32 v[150:151], v[82:83], v[150:151]
	s_branch .LBB0_254

.LBB0_254:
	s_and_b64 vcc, exec, s[8:9]
	v_cvt_pk_bf16_f32 v172, v148, v149
	v_cvt_pk_bf16_f32 v173, v146, v147
	v_cvt_pk_bf16_f32 v174, v152, v153
	v_cvt_pk_bf16_f32 v175, v150, v151
	global_store_dwordx4 v[144:145], v[172:175], off offset:256 sc1
	s_cbranch_vccnz .LBB0_256
	v_pk_mul_f32 v[146:147], v[76:77], v[76:77]
	v_pk_mul_f32 v[144:145], v[78:79], v[78:79]
	v_pk_fma_f32 v[146:147], v[140:141], v[146:147], v[138:139]
	v_pk_mul_f32 v[150:151], v[68:69], v[68:69]
	v_pk_mul_f32 v[146:147], v[76:77], v[146:147]
	v_pk_fma_f32 v[144:145], v[140:141], v[144:145], v[138:139]
	v_exp_f32_e32 v146, v146
	v_exp_f32_e32 v147, v147
	v_pk_fma_f32 v[150:151], v[140:141], v[150:151], v[138:139]
	v_pk_mul_f32 v[144:145], v[78:79], v[144:145]
	v_pk_mul_f32 v[150:151], v[68:69], v[150:151]
	v_pk_add_f32 v[146:147], v[146:147], 1.0 op_sel_hi:[1,0]
	v_exp_f32_e32 v144, v144
	v_rcp_f32_e32 v148, v146
	v_rcp_f32_e32 v149, v147
	v_pk_mul_f32 v[146:147], v[70:71], v[70:71]
	v_exp_f32_e32 v145, v145
	v_pk_fma_f32 v[146:147], v[140:141], v[146:147], v[138:139]
	v_exp_f32_e32 v150, v150
	v_pk_mul_f32 v[146:147], v[70:71], v[146:147]
	v_exp_f32_e32 v151, v151
	v_exp_f32_e32 v146, v146
	v_exp_f32_e32 v147, v147
	v_pk_add_f32 v[144:145], v[144:145], 1.0 op_sel_hi:[1,0]
	v_pk_add_f32 v[150:151], v[150:151], 1.0 op_sel_hi:[1,0]
	v_rcp_f32_e32 v144, v144
	v_pk_add_f32 v[146:147], v[146:147], 1.0 op_sel_hi:[1,0]
	v_rcp_f32_e32 v145, v145
	v_rcp_f32_e32 v152, v150
	v_rcp_f32_e32 v153, v151
	v_rcp_f32_e32 v150, v146
	v_rcp_f32_e32 v151, v147
	v_pk_mul_f32 v[146:147], v[78:79], v[144:145]
	v_pk_mul_f32 v[148:149], v[76:77], v[148:149]
	v_pk_mul_f32 v[152:153], v[68:69], v[152:153]
	v_pk_mul_f32 v[150:151], v[70:71], v[150:151]
	s_branch .LBB0_257

.LBB0_257:
	v_or_b32_e32 v144, 48, v136
	v_ashrrev_i32_e32 v145, 31, v144
	v_lshlrev_b64 v[144:145], 12, v[144:145]
	v_lshl_add_u64 v[144:145], v[142:143], 0, v[144:145]
	s_and_b64 vcc, exec, s[8:9]
	v_cvt_pk_bf16_f32 v172, v148, v149
	v_cvt_pk_bf16_f32 v173, v146, v147
	v_cvt_pk_bf16_f32 v174, v152, v153
	v_cvt_pk_bf16_f32 v175, v150, v151
	global_store_dwordx4 v[144:145], v[172:175], off sc1
	s_cbranch_vccnz .LBB0_259
	v_pk_mul_f32 v[146:147], v[74:75], v[74:75]
	v_pk_mul_f32 v[148:149], v[72:73], v[72:73]
	v_pk_mul_f32 v[150:151], v[66:67], v[66:67]
	v_pk_mul_f32 v[152:153], v[64:65], v[64:65]
	v_pk_fma_f32 v[148:149], v[140:141], v[148:149], v[138:139]
	v_pk_fma_f32 v[146:147], v[140:141], v[146:147], v[138:139]
	v_pk_fma_f32 v[152:153], v[140:141], v[152:153], v[138:139]
	v_pk_fma_f32 v[150:151], v[140:141], v[150:151], v[138:139]
	v_pk_mul_f32 v[148:149], v[72:73], v[148:149]
	v_pk_mul_f32 v[146:147], v[74:75], v[146:147]
	v_pk_mul_f32 v[152:153], v[64:65], v[152:153]
	v_pk_mul_f32 v[150:151], v[66:67], v[150:151]
	v_exp_f32_e32 v148, v148
	v_exp_f32_e32 v149, v149
	v_exp_f32_e32 v146, v146
	v_exp_f32_e32 v147, v147
	v_exp_f32_e32 v152, v152
	v_exp_f32_e32 v153, v153
	v_exp_f32_e32 v150, v150
	v_exp_f32_e32 v151, v151
	v_pk_add_f32 v[148:149], v[148:149], 1.0 op_sel_hi:[1,0]
	v_pk_add_f32 v[146:147], v[146:147], 1.0 op_sel_hi:[1,0]
	v_pk_add_f32 v[152:153], v[152:153], 1.0 op_sel_hi:[1,0]
	v_pk_add_f32 v[150:151], v[150:151], 1.0 op_sel_hi:[1,0]
	v_rcp_f32_e32 v148, v148
	v_rcp_f32_e32 v149, v149
	v_rcp_f32_e32 v146, v146
	v_rcp_f32_e32 v147, v147
	v_rcp_f32_e32 v152, v152
	v_rcp_f32_e32 v153, v153
	v_rcp_f32_e32 v150, v150
	v_rcp_f32_e32 v151, v151
	v_pk_mul_f32 v[146:147], v[74:75], v[146:147]
	v_pk_mul_f32 v[148:149], v[72:73], v[148:149]
	v_pk_mul_f32 v[152:153], v[64:65], v[152:153]
	v_pk_mul_f32 v[150:151], v[66:67], v[150:151]
	s_branch .LBB0_260

.LBB0_260:
	s_and_b64 vcc, exec, s[8:9]
	v_cvt_pk_bf16_f32 v172, v148, v149
	v_cvt_pk_bf16_f32 v173, v146, v147
	v_cvt_pk_bf16_f32 v174, v152, v153
	v_cvt_pk_bf16_f32 v175, v150, v151
	global_store_dwordx4 v[144:145], v[172:175], off offset:256 sc1
	s_cbranch_vccnz .LBB0_262
	v_pk_mul_f32 v[146:147], v[60:61], v[60:61]
	v_pk_mul_f32 v[144:145], v[62:63], v[62:63]
	v_pk_fma_f32 v[146:147], v[140:141], v[146:147], v[138:139]
	v_pk_mul_f32 v[150:151], v[52:53], v[52:53]
	v_pk_mul_f32 v[146:147], v[60:61], v[146:147]
	v_pk_fma_f32 v[144:145], v[140:141], v[144:145], v[138:139]
	v_exp_f32_e32 v146, v146
	v_exp_f32_e32 v147, v147
	v_pk_fma_f32 v[150:151], v[140:141], v[150:151], v[138:139]
	v_pk_mul_f32 v[144:145], v[62:63], v[144:145]
	v_pk_mul_f32 v[150:151], v[52:53], v[150:151]
	v_pk_add_f32 v[146:147], v[146:147], 1.0 op_sel_hi:[1,0]
	v_exp_f32_e32 v144, v144
	v_rcp_f32_e32 v148, v146
	v_rcp_f32_e32 v149, v147
	v_pk_mul_f32 v[146:147], v[54:55], v[54:55]
	v_exp_f32_e32 v145, v145
	v_pk_fma_f32 v[146:147], v[140:141], v[146:147], v[138:139]
	v_exp_f32_e32 v150, v150
	v_pk_mul_f32 v[146:147], v[54:55], v[146:147]
	v_exp_f32_e32 v151, v151
	v_exp_f32_e32 v146, v146
	v_exp_f32_e32 v147, v147
	v_pk_add_f32 v[144:145], v[144:145], 1.0 op_sel_hi:[1,0]
	v_pk_add_f32 v[150:151], v[150:151], 1.0 op_sel_hi:[1,0]
	v_rcp_f32_e32 v144, v144
	v_pk_add_f32 v[146:147], v[146:147], 1.0 op_sel_hi:[1,0]
	v_rcp_f32_e32 v145, v145
	v_rcp_f32_e32 v152, v150
	v_rcp_f32_e32 v153, v151
	v_rcp_f32_e32 v150, v146
	v_rcp_f32_e32 v151, v147
	v_pk_mul_f32 v[146:147], v[62:63], v[144:145]
	v_pk_mul_f32 v[148:149], v[60:61], v[148:149]
	v_pk_mul_f32 v[152:153], v[52:53], v[152:153]
	v_pk_mul_f32 v[150:151], v[54:55], v[150:151]
	s_branch .LBB0_263

.LBB0_263:
	v_lshlrev_b64 v[144:145], 12, v[136:137]
	v_lshl_add_u64 v[144:145], v[142:143], 0, v[144:145]
	v_cvt_pk_bf16_f32 v173, v146, v147
	v_add_co_u32_e32 v146, vcc, 0x80000, v144
	v_cvt_pk_bf16_f32 v172, v148, v149
	v_cvt_pk_bf16_f32 v174, v152, v153
	v_cvt_pk_bf16_f32 v175, v150, v151
	s_nop 1
	v_addc_co_u32_e32 v147, vcc, 0, v145, vcc
	s_and_b64 vcc, exec, s[8:9]
	global_store_dwordx4 v[146:147], v[172:175], off sc1
	s_cbranch_vccnz .LBB0_265
	v_pk_mul_f32 v[146:147], v[58:59], v[58:59]
	v_pk_mul_f32 v[148:149], v[56:57], v[56:57]
	v_pk_mul_f32 v[150:151], v[50:51], v[50:51]
	v_pk_mul_f32 v[152:153], v[48:49], v[48:49]
	v_pk_fma_f32 v[148:149], v[140:141], v[148:149], v[138:139]
	v_pk_fma_f32 v[146:147], v[140:141], v[146:147], v[138:139]
	v_pk_fma_f32 v[152:153], v[140:141], v[152:153], v[138:139]
	v_pk_fma_f32 v[150:151], v[140:141], v[150:151], v[138:139]
	v_pk_mul_f32 v[148:149], v[56:57], v[148:149]
	v_pk_mul_f32 v[146:147], v[58:59], v[146:147]
	v_pk_mul_f32 v[152:153], v[48:49], v[152:153]
	v_pk_mul_f32 v[150:151], v[50:51], v[150:151]
	v_exp_f32_e32 v148, v148
	v_exp_f32_e32 v149, v149
	v_exp_f32_e32 v146, v146
	v_exp_f32_e32 v147, v147
	v_exp_f32_e32 v152, v152
	v_exp_f32_e32 v153, v153
	v_exp_f32_e32 v150, v150
	v_exp_f32_e32 v151, v151
	v_pk_add_f32 v[148:149], v[148:149], 1.0 op_sel_hi:[1,0]
	v_pk_add_f32 v[146:147], v[146:147], 1.0 op_sel_hi:[1,0]
	v_pk_add_f32 v[152:153], v[152:153], 1.0 op_sel_hi:[1,0]
	v_pk_add_f32 v[150:151], v[150:151], 1.0 op_sel_hi:[1,0]
	v_rcp_f32_e32 v148, v148
	v_rcp_f32_e32 v149, v149
	v_rcp_f32_e32 v146, v146
	v_rcp_f32_e32 v147, v147
	v_rcp_f32_e32 v152, v152
	v_rcp_f32_e32 v153, v153
	v_rcp_f32_e32 v150, v150
	v_rcp_f32_e32 v151, v151
	v_pk_mul_f32 v[146:147], v[58:59], v[146:147]
	v_pk_mul_f32 v[148:149], v[56:57], v[148:149]
	v_pk_mul_f32 v[152:153], v[48:49], v[152:153]
	v_pk_mul_f32 v[150:151], v[50:51], v[150:151]
	s_branch .LBB0_266

.LBB0_266:
	s_mov_b64 s[10:11], 0x80000
	v_lshl_add_u64 v[172:173], v[144:145], 0, s[10:11]
	s_and_b64 vcc, exec, s[8:9]
	v_cvt_pk_bf16_f32 v144, v148, v149
	v_cvt_pk_bf16_f32 v145, v146, v147
	v_cvt_pk_bf16_f32 v146, v152, v153
	v_cvt_pk_bf16_f32 v147, v150, v151
	global_store_dwordx4 v[172:173], v[144:147], off offset:256 sc1
	s_cbranch_vccnz .LBB0_268
	s_nop 0
	v_pk_mul_f32 v[146:147], v[44:45], v[44:45]
	v_pk_mul_f32 v[144:145], v[46:47], v[46:47]
	v_pk_fma_f32 v[146:147], v[140:141], v[146:147], v[138:139]
	v_pk_mul_f32 v[150:151], v[36:37], v[36:37]
	v_pk_mul_f32 v[146:147], v[44:45], v[146:147]
	v_pk_fma_f32 v[144:145], v[140:141], v[144:145], v[138:139]
	v_exp_f32_e32 v146, v146
	v_exp_f32_e32 v147, v147
	v_pk_fma_f32 v[150:151], v[140:141], v[150:151], v[138:139]
	v_pk_mul_f32 v[144:145], v[46:47], v[144:145]
	v_pk_mul_f32 v[150:151], v[36:37], v[150:151]
	v_pk_add_f32 v[146:147], v[146:147], 1.0 op_sel_hi:[1,0]
	v_exp_f32_e32 v144, v144
	v_rcp_f32_e32 v148, v146
	v_rcp_f32_e32 v149, v147
	v_pk_mul_f32 v[146:147], v[38:39], v[38:39]
	v_exp_f32_e32 v145, v145
	v_pk_fma_f32 v[146:147], v[140:141], v[146:147], v[138:139]
	v_exp_f32_e32 v150, v150
	v_pk_mul_f32 v[146:147], v[38:39], v[146:147]
	v_exp_f32_e32 v151, v151
	v_exp_f32_e32 v146, v146
	v_exp_f32_e32 v147, v147
	v_pk_add_f32 v[144:145], v[144:145], 1.0 op_sel_hi:[1,0]
	v_pk_add_f32 v[150:151], v[150:151], 1.0 op_sel_hi:[1,0]
	v_rcp_f32_e32 v144, v144
	v_pk_add_f32 v[146:147], v[146:147], 1.0 op_sel_hi:[1,0]
	v_rcp_f32_e32 v145, v145
	v_rcp_f32_e32 v152, v150
	v_rcp_f32_e32 v153, v151
	v_rcp_f32_e32 v150, v146
	v_rcp_f32_e32 v151, v147
	v_pk_mul_f32 v[146:147], v[46:47], v[144:145]
	v_pk_mul_f32 v[148:149], v[44:45], v[148:149]
	v_pk_mul_f32 v[152:153], v[36:37], v[152:153]
	v_pk_mul_f32 v[150:151], v[38:39], v[150:151]
	s_branch .LBB0_269

.LBB0_269:
	v_lshlrev_b64 v[144:145], 12, v[136:137]
	v_lshl_add_u64 v[144:145], v[142:143], 0, v[144:145]
	v_cvt_pk_bf16_f32 v173, v146, v147
	v_add_co_u32_e32 v146, vcc, 0x90000, v144
	v_cvt_pk_bf16_f32 v172, v148, v149
	v_cvt_pk_bf16_f32 v174, v152, v153
	v_cvt_pk_bf16_f32 v175, v150, v151
	s_nop 1
	v_addc_co_u32_e32 v147, vcc, 0, v145, vcc
	s_and_b64 vcc, exec, s[8:9]
	global_store_dwordx4 v[146:147], v[172:175], off sc1
	s_cbranch_vccnz .LBB0_271
	v_pk_mul_f32 v[146:147], v[42:43], v[42:43]
	v_pk_mul_f32 v[148:149], v[40:41], v[40:41]
	v_pk_mul_f32 v[150:151], v[34:35], v[34:35]
	v_pk_mul_f32 v[152:153], v[32:33], v[32:33]
	v_pk_fma_f32 v[148:149], v[140:141], v[148:149], v[138:139]
	v_pk_fma_f32 v[146:147], v[140:141], v[146:147], v[138:139]
	v_pk_fma_f32 v[152:153], v[140:141], v[152:153], v[138:139]
	v_pk_fma_f32 v[150:151], v[140:141], v[150:151], v[138:139]
	v_pk_mul_f32 v[148:149], v[40:41], v[148:149]
	v_pk_mul_f32 v[146:147], v[42:43], v[146:147]
	v_pk_mul_f32 v[152:153], v[32:33], v[152:153]
	v_pk_mul_f32 v[150:151], v[34:35], v[150:151]
	v_exp_f32_e32 v148, v148
	v_exp_f32_e32 v149, v149
	v_exp_f32_e32 v146, v146
	v_exp_f32_e32 v147, v147
	v_exp_f32_e32 v152, v152
	v_exp_f32_e32 v153, v153
	v_exp_f32_e32 v150, v150
	v_exp_f32_e32 v151, v151
	v_pk_add_f32 v[148:149], v[148:149], 1.0 op_sel_hi:[1,0]
	v_pk_add_f32 v[146:147], v[146:147], 1.0 op_sel_hi:[1,0]
	v_pk_add_f32 v[152:153], v[152:153], 1.0 op_sel_hi:[1,0]
	v_pk_add_f32 v[150:151], v[150:151], 1.0 op_sel_hi:[1,0]
	v_rcp_f32_e32 v148, v148
	v_rcp_f32_e32 v149, v149
	v_rcp_f32_e32 v146, v146
	v_rcp_f32_e32 v147, v147
	v_rcp_f32_e32 v152, v152
	v_rcp_f32_e32 v153, v153
	v_rcp_f32_e32 v150, v150
	v_rcp_f32_e32 v151, v151
	v_pk_mul_f32 v[146:147], v[42:43], v[146:147]
	v_pk_mul_f32 v[148:149], v[40:41], v[148:149]
	v_pk_mul_f32 v[152:153], v[32:33], v[152:153]
	v_pk_mul_f32 v[150:151], v[34:35], v[150:151]
	s_branch .LBB0_272

.LBB0_272:
	s_mov_b64 s[10:11], 0x90000
	v_lshl_add_u64 v[172:173], v[144:145], 0, s[10:11]
	s_and_b64 vcc, exec, s[8:9]
	v_cvt_pk_bf16_f32 v144, v148, v149
	v_cvt_pk_bf16_f32 v145, v146, v147
	v_cvt_pk_bf16_f32 v146, v152, v153
	v_cvt_pk_bf16_f32 v147, v150, v151
	global_store_dwordx4 v[172:173], v[144:147], off offset:256 sc1
	s_cbranch_vccnz .LBB0_274
	s_nop 0
	v_pk_mul_f32 v[146:147], v[28:29], v[28:29]
	v_pk_mul_f32 v[144:145], v[30:31], v[30:31]
	v_pk_fma_f32 v[146:147], v[140:141], v[146:147], v[138:139]
	v_pk_mul_f32 v[150:151], v[20:21], v[20:21]
	v_pk_mul_f32 v[146:147], v[28:29], v[146:147]
	v_pk_fma_f32 v[144:145], v[140:141], v[144:145], v[138:139]
	v_exp_f32_e32 v146, v146
	v_exp_f32_e32 v147, v147
	v_pk_fma_f32 v[150:151], v[140:141], v[150:151], v[138:139]
	v_pk_mul_f32 v[144:145], v[30:31], v[144:145]
	v_pk_mul_f32 v[150:151], v[20:21], v[150:151]
	v_pk_add_f32 v[146:147], v[146:147], 1.0 op_sel_hi:[1,0]
	v_exp_f32_e32 v144, v144
	v_rcp_f32_e32 v148, v146
	v_rcp_f32_e32 v149, v147
	v_pk_mul_f32 v[146:147], v[22:23], v[22:23]
	v_exp_f32_e32 v145, v145
	v_pk_fma_f32 v[146:147], v[140:141], v[146:147], v[138:139]
	v_exp_f32_e32 v150, v150
	v_pk_mul_f32 v[146:147], v[22:23], v[146:147]
	v_exp_f32_e32 v151, v151
	v_exp_f32_e32 v146, v146
	v_exp_f32_e32 v147, v147
	v_pk_add_f32 v[144:145], v[144:145], 1.0 op_sel_hi:[1,0]
	v_pk_add_f32 v[150:151], v[150:151], 1.0 op_sel_hi:[1,0]
	v_rcp_f32_e32 v144, v144
	v_pk_add_f32 v[146:147], v[146:147], 1.0 op_sel_hi:[1,0]
	v_rcp_f32_e32 v145, v145
	v_rcp_f32_e32 v152, v150
	v_rcp_f32_e32 v153, v151
	v_rcp_f32_e32 v150, v146
	v_rcp_f32_e32 v151, v147
	v_pk_mul_f32 v[146:147], v[30:31], v[144:145]
	v_pk_mul_f32 v[148:149], v[28:29], v[148:149]
	v_pk_mul_f32 v[152:153], v[20:21], v[152:153]
	v_pk_mul_f32 v[150:151], v[22:23], v[150:151]
	s_branch .LBB0_275

.LBB0_275:
	v_lshlrev_b64 v[144:145], 12, v[136:137]
	v_lshl_add_u64 v[144:145], v[142:143], 0, v[144:145]
	v_cvt_pk_bf16_f32 v173, v146, v147
	v_add_co_u32_e32 v146, vcc, 0xa0000, v144
	v_cvt_pk_bf16_f32 v172, v148, v149
	v_cvt_pk_bf16_f32 v174, v152, v153
	v_cvt_pk_bf16_f32 v175, v150, v151
	s_nop 1
	v_addc_co_u32_e32 v147, vcc, 0, v145, vcc
	s_and_b64 vcc, exec, s[8:9]
	global_store_dwordx4 v[146:147], v[172:175], off sc1
	s_cbranch_vccnz .LBB0_277
	v_pk_mul_f32 v[146:147], v[26:27], v[26:27]
	v_pk_mul_f32 v[148:149], v[24:25], v[24:25]
	v_pk_mul_f32 v[150:151], v[18:19], v[18:19]
	v_pk_mul_f32 v[152:153], v[16:17], v[16:17]
	v_pk_fma_f32 v[148:149], v[140:141], v[148:149], v[138:139]
	v_pk_fma_f32 v[146:147], v[140:141], v[146:147], v[138:139]
	v_pk_fma_f32 v[152:153], v[140:141], v[152:153], v[138:139]
	v_pk_fma_f32 v[150:151], v[140:141], v[150:151], v[138:139]
	v_pk_mul_f32 v[148:149], v[24:25], v[148:149]
	v_pk_mul_f32 v[146:147], v[26:27], v[146:147]
	v_pk_mul_f32 v[152:153], v[16:17], v[152:153]
	v_pk_mul_f32 v[150:151], v[18:19], v[150:151]
	v_exp_f32_e32 v148, v148
	v_exp_f32_e32 v149, v149
	v_exp_f32_e32 v146, v146
	v_exp_f32_e32 v147, v147
	v_exp_f32_e32 v152, v152
	v_exp_f32_e32 v153, v153
	v_exp_f32_e32 v150, v150
	v_exp_f32_e32 v151, v151
	v_pk_add_f32 v[148:149], v[148:149], 1.0 op_sel_hi:[1,0]
	v_pk_add_f32 v[146:147], v[146:147], 1.0 op_sel_hi:[1,0]
	v_pk_add_f32 v[152:153], v[152:153], 1.0 op_sel_hi:[1,0]
	v_pk_add_f32 v[150:151], v[150:151], 1.0 op_sel_hi:[1,0]
	v_rcp_f32_e32 v148, v148
	v_rcp_f32_e32 v149, v149
	v_rcp_f32_e32 v146, v146
	v_rcp_f32_e32 v147, v147
	v_rcp_f32_e32 v152, v152
	v_rcp_f32_e32 v153, v153
	v_rcp_f32_e32 v150, v150
	v_rcp_f32_e32 v151, v151
	v_pk_mul_f32 v[146:147], v[26:27], v[146:147]
	v_pk_mul_f32 v[148:149], v[24:25], v[148:149]
	v_pk_mul_f32 v[152:153], v[16:17], v[152:153]
	v_pk_mul_f32 v[150:151], v[18:19], v[150:151]
	s_branch .LBB0_278

.LBB0_278:
	s_mov_b64 s[10:11], 0xa0000
	v_lshl_add_u64 v[172:173], v[144:145], 0, s[10:11]
	s_and_b64 vcc, exec, s[8:9]
	v_cvt_pk_bf16_f32 v144, v148, v149
	v_cvt_pk_bf16_f32 v145, v146, v147
	v_cvt_pk_bf16_f32 v146, v152, v153
	v_cvt_pk_bf16_f32 v147, v150, v151
	global_store_dwordx4 v[172:173], v[144:147], off offset:256 sc1
	s_cbranch_vccnz .LBB0_280
	s_nop 0
	v_pk_mul_f32 v[144:145], v[14:15], v[14:15]
	v_pk_mul_f32 v[146:147], v[12:13], v[12:13]
	v_pk_mul_f32 v[148:149], v[6:7], v[6:7]
	v_pk_mul_f32 v[150:151], v[4:5], v[4:5]
	v_pk_fma_f32 v[146:147], v[140:141], v[146:147], v[138:139]
	v_pk_fma_f32 v[144:145], v[140:141], v[144:145], v[138:139]
	v_pk_fma_f32 v[150:151], v[140:141], v[150:151], v[138:139]
	v_pk_fma_f32 v[148:149], v[140:141], v[148:149], v[138:139]
	v_pk_mul_f32 v[146:147], v[12:13], v[146:147]
	v_pk_mul_f32 v[144:145], v[14:15], v[144:145]
	v_pk_mul_f32 v[150:151], v[4:5], v[150:151]
	v_pk_mul_f32 v[148:149], v[6:7], v[148:149]
	v_exp_f32_e32 v146, v146
	v_exp_f32_e32 v147, v147
	v_exp_f32_e32 v144, v144
	v_exp_f32_e32 v145, v145
	v_exp_f32_e32 v150, v150
	v_exp_f32_e32 v151, v151
	v_exp_f32_e32 v148, v148
	v_exp_f32_e32 v149, v149
	v_pk_add_f32 v[146:147], v[146:147], 1.0 op_sel_hi:[1,0]
	v_pk_add_f32 v[144:145], v[144:145], 1.0 op_sel_hi:[1,0]
	v_pk_add_f32 v[150:151], v[150:151], 1.0 op_sel_hi:[1,0]
	v_pk_add_f32 v[148:149], v[148:149], 1.0 op_sel_hi:[1,0]
	v_rcp_f32_e32 v146, v146
	v_rcp_f32_e32 v147, v147
	v_rcp_f32_e32 v144, v144
	v_rcp_f32_e32 v145, v145
	v_rcp_f32_e32 v150, v150
	v_rcp_f32_e32 v151, v151
	v_rcp_f32_e32 v148, v148
	v_rcp_f32_e32 v149, v149
	v_pk_mul_f32 v[144:145], v[14:15], v[144:145]
	v_pk_mul_f32 v[146:147], v[12:13], v[146:147]
	v_pk_mul_f32 v[150:151], v[4:5], v[150:151]
	v_pk_mul_f32 v[148:149], v[6:7], v[148:149]
	s_branch .LBB0_281

.LBB0_281:
	v_lshlrev_b64 v[152:153], 12, v[136:137]
	v_lshl_add_u64 v[142:143], v[142:143], 0, v[152:153]
	v_cvt_pk_bf16_f32 v173, v144, v145
	v_add_co_u32_e32 v144, vcc, 0xb0000, v142
	v_cvt_pk_bf16_f32 v172, v146, v147
	v_cvt_pk_bf16_f32 v174, v150, v151
	v_cvt_pk_bf16_f32 v175, v148, v149
	s_nop 1
	v_addc_co_u32_e32 v145, vcc, 0, v143, vcc
	s_and_b64 vcc, exec, s[8:9]
	global_store_dwordx4 v[144:145], v[172:175], off sc1
	s_cbranch_vccnz .LBB0_283
	v_pk_mul_f32 v[144:145], v[10:11], v[10:11]
	v_pk_mul_f32 v[146:147], v[8:9], v[8:9]
	v_pk_mul_f32 v[148:149], v[2:3], v[2:3]
	v_pk_mul_f32 v[150:151], v[0:1], v[0:1]
	v_pk_fma_f32 v[146:147], v[140:141], v[146:147], v[138:139]
	v_pk_fma_f32 v[144:145], v[140:141], v[144:145], v[138:139]
	v_pk_fma_f32 v[150:151], v[140:141], v[150:151], v[138:139]
	v_pk_fma_f32 v[138:139], v[140:141], v[148:149], v[138:139]
	v_pk_mul_f32 v[146:147], v[8:9], v[146:147]
	v_pk_mul_f32 v[144:145], v[10:11], v[144:145]
	v_pk_mul_f32 v[150:151], v[0:1], v[150:151]
	v_pk_mul_f32 v[138:139], v[2:3], v[138:139]
	v_exp_f32_e32 v146, v146
	v_exp_f32_e32 v147, v147
	v_exp_f32_e32 v144, v144
	v_exp_f32_e32 v145, v145
	v_exp_f32_e32 v150, v150
	v_exp_f32_e32 v151, v151
	v_exp_f32_e32 v138, v138
	v_exp_f32_e32 v139, v139
	v_pk_add_f32 v[146:147], v[146:147], 1.0 op_sel_hi:[1,0]
	v_pk_add_f32 v[144:145], v[144:145], 1.0 op_sel_hi:[1,0]
	v_pk_add_f32 v[150:151], v[150:151], 1.0 op_sel_hi:[1,0]
	v_pk_add_f32 v[138:139], v[138:139], 1.0 op_sel_hi:[1,0]
	v_rcp_f32_e32 v146, v146
	v_rcp_f32_e32 v147, v147
	v_rcp_f32_e32 v144, v144
	v_rcp_f32_e32 v145, v145
	v_rcp_f32_e32 v150, v150
	v_rcp_f32_e32 v151, v151
	v_rcp_f32_e32 v140, v138
	v_rcp_f32_e32 v141, v139
	v_pk_mul_f32 v[138:139], v[10:11], v[144:145]
	v_pk_mul_f32 v[144:145], v[8:9], v[146:147]
	v_pk_mul_f32 v[146:147], v[0:1], v[150:151]
	v_pk_mul_f32 v[140:141], v[2:3], v[140:141]
	s_branch .LBB0_284

.LBB0_284:
	s_mov_b64 s[8:9], 0xb0000
	v_lshl_add_u64 v[148:149], v[142:143], 0, s[8:9]
	v_cvt_pk_bf16_f32 v142, v144, v145
	v_cvt_pk_bf16_f32 v143, v138, v139
	v_cvt_pk_bf16_f32 v144, v146, v147
	v_cvt_pk_bf16_f32 v145, v140, v141
	global_store_dwordx4 v[148:149], v[142:145], off offset:256 sc1
	s_mov_b64 s[8:9], 0
.LBB0_285:
	s_and_b64 vcc, exec, s[8:9]
	s_cbranch_vccz .LBB0_230
	s_mov_b32 s8, 0xc0135761
	v_pk_mul_f32 v[142:143], v[124:125], v[124:125]
	v_mov_b64_e32 v[138:139], s[8:9]
	v_pk_mul_f32 v[144:145], v[120:121], v[120:121]
	v_pk_fma_f32 v[142:143], v[142:143], s[90:91], v[138:139] op_sel_hi:[1,0,0] neg_lo:[1,0,0] neg_hi:[1,0,0]
	v_pk_fma_f32 v[144:145], v[144:145], 0, s[88:89] op_sel_hi:[1,0,0]
	v_pk_mul_f32 v[142:143], v[124:125], v[142:143]
	v_pk_mul_f32 v[144:145], v[120:121], v[144:145]
	v_exp_f32_e32 v142, v142
	v_exp_f32_e32 v143, v143
	v_exp_f32_e32 v144, v144
	v_exp_f32_e32 v145, v145
	v_pk_mul_f32 v[146:147], v[126:127], v[126:127]
	v_pk_add_f32 v[142:143], v[142:143], 1.0 op_sel_hi:[1,0]
	v_lshl_or_b32 v140, s92, 7, v166
	v_pk_add_f32 v[144:145], v[144:145], 1.0 op_sel_hi:[1,0]
	v_rcp_f32_e32 v142, v142
	v_rcp_f32_e32 v143, v143
	v_rcp_f32_e32 v144, v144
	v_rcp_f32_e32 v145, v145
	v_ashrrev_i32_e32 v137, 31, v136
	v_pk_mul_f32 v[124:125], v[124:125], v[142:143]
	v_pk_mul_f32 v[142:143], v[122:123], v[122:123]
	v_pk_mul_f32 v[120:121], v[120:121], v[144:145]
	v_pk_fma_f32 v[142:143], v[142:143], 0, s[88:89] op_sel_hi:[1,0,0]
	v_pk_mul_f32 v[120:121], v[124:125], v[120:121]
	v_pk_fma_f32 v[124:125], v[146:147], s[90:91], v[138:139] op_sel_hi:[1,0,0] neg_lo:[1,0,0] neg_hi:[1,0,0]
	v_pk_mul_f32 v[142:143], v[122:123], v[142:143]
	v_pk_mul_f32 v[124:125], v[126:127], v[124:125]
	v_exp_f32_e32 v142, v142
	v_exp_f32_e32 v124, v124
	v_exp_f32_e32 v125, v125
	v_exp_f32_e32 v143, v143
	v_pk_mul_f32 v[144:145], v[116:117], v[116:117]
	v_ashrrev_i32_e32 v141, 31, v140
	v_pk_add_f32 v[124:125], v[124:125], 1.0 op_sel_hi:[1,0]
	v_pk_add_f32 v[142:143], v[142:143], 1.0 op_sel_hi:[1,0]
	v_pk_fma_f32 v[144:145], v[144:145], s[90:91], v[138:139] op_sel_hi:[1,0,0] neg_lo:[1,0,0] neg_hi:[1,0,0]
	v_rcp_f32_e32 v124, v124
	v_rcp_f32_e32 v125, v125
	v_rcp_f32_e32 v142, v142
	v_rcp_f32_e32 v143, v143
	v_pk_mul_f32 v[144:145], v[116:117], v[144:145]
	v_pk_mul_f32 v[124:125], v[126:127], v[124:125]
	v_exp_f32_e32 v144, v144
	v_exp_f32_e32 v145, v145
	v_pk_mul_f32 v[122:123], v[122:123], v[142:143]
	v_pk_mul_f32 v[126:127], v[112:113], v[112:113]
	v_pk_mul_f32 v[122:123], v[124:125], v[122:123]
	v_pk_add_f32 v[124:125], v[144:145], 1.0 op_sel_hi:[1,0]
	v_pk_fma_f32 v[126:127], v[126:127], 0, s[88:89] op_sel_hi:[1,0,0]
	v_rcp_f32_e32 v124, v124
	v_rcp_f32_e32 v125, v125
	v_pk_mul_f32 v[142:143], v[118:119], v[118:119]
	v_pk_mul_f32 v[126:127], v[112:113], v[126:127]
	v_pk_fma_f32 v[142:143], v[142:143], s[90:91], v[138:139] op_sel_hi:[1,0,0] neg_lo:[1,0,0] neg_hi:[1,0,0]
	v_pk_mul_f32 v[116:117], v[116:117], v[124:125]
	v_pk_mul_f32 v[124:125], v[114:115], v[114:115]
	v_exp_f32_e32 v126, v126
	v_pk_fma_f32 v[124:125], v[124:125], 0, s[88:89] op_sel_hi:[1,0,0]
	v_exp_f32_e32 v127, v127
	v_pk_mul_f32 v[142:143], v[118:119], v[142:143]
	v_pk_mul_f32 v[124:125], v[114:115], v[124:125]
	v_exp_f32_e32 v142, v142
	v_exp_f32_e32 v143, v143
	v_exp_f32_e32 v124, v124
	v_exp_f32_e32 v125, v125
	v_pk_add_f32 v[126:127], v[126:127], 1.0 op_sel_hi:[1,0]
	v_pk_add_f32 v[142:143], v[142:143], 1.0 op_sel_hi:[1,0]
	v_rcp_f32_e32 v126, v126
	v_rcp_f32_e32 v127, v127
	v_pk_add_f32 v[124:125], v[124:125], 1.0 op_sel_hi:[1,0]
	v_rcp_f32_e32 v142, v142
	v_rcp_f32_e32 v143, v143
	v_rcp_f32_e32 v124, v124
	v_rcp_f32_e32 v125, v125
	v_pk_mul_f32 v[112:113], v[112:113], v[126:127]
	s_mov_b32 s3, 0x80000
	v_pk_mul_f32 v[112:113], v[116:117], v[112:113]
	v_pk_mul_f32 v[116:117], v[118:119], v[142:143]
	v_pk_mul_f32 v[114:115], v[114:115], v[124:125]
	v_cvt_pk_bf16_f32 v118, v112, v113
	v_lshlrev_b64 v[112:113], 12, v[136:137]
	v_pk_mul_f32 v[114:115], v[116:117], v[114:115]
	v_lshl_add_u64 v[112:113], s[58:59], 0, v[112:113]
	v_cvt_pk_bf16_f32 v119, v114, v115
	v_lshlrev_b64 v[114:115], 1, v[140:141]
	v_cvt_pk_bf16_f32 v116, v120, v121
	v_cvt_pk_bf16_f32 v117, v122, v123
	v_lshl_add_u64 v[112:113], v[112:113], 0, v[114:115]
	global_store_dwordx4 v[112:113], v[116:119], off sc1
	v_pk_mul_f32 v[120:121], v[110:111], v[110:111]
	s_nop 0
	v_pk_mul_f32 v[116:117], v[108:109], v[108:109]
	v_pk_mul_f32 v[118:119], v[104:105], v[104:105]
	v_pk_fma_f32 v[116:117], v[116:117], s[90:91], v[138:139] op_sel_hi:[1,0,0] neg_lo:[1,0,0] neg_hi:[1,0,0]
	v_pk_fma_f32 v[118:119], v[118:119], 0, s[88:89] op_sel_hi:[1,0,0]
	v_pk_mul_f32 v[116:117], v[108:109], v[116:117]
	v_pk_mul_f32 v[118:119], v[104:105], v[118:119]
	v_exp_f32_e32 v116, v116
	v_exp_f32_e32 v117, v117
	v_exp_f32_e32 v118, v118
	v_exp_f32_e32 v119, v119
	v_pk_add_f32 v[116:117], v[116:117], 1.0 op_sel_hi:[1,0]
	s_nop 0
	v_rcp_f32_e32 v116, v116
	v_pk_add_f32 v[118:119], v[118:119], 1.0 op_sel_hi:[1,0]
	v_rcp_f32_e32 v117, v117
	v_rcp_f32_e32 v118, v118
	v_rcp_f32_e32 v119, v119
	v_pk_mul_f32 v[108:109], v[108:109], v[116:117]
	v_pk_mul_f32 v[116:117], v[106:107], v[106:107]
	v_pk_mul_f32 v[104:105], v[104:105], v[118:119]
	v_pk_fma_f32 v[116:117], v[116:117], 0, s[88:89] op_sel_hi:[1,0,0]
	v_pk_mul_f32 v[104:105], v[108:109], v[104:105]
	v_pk_fma_f32 v[108:109], v[120:121], s[90:91], v[138:139] op_sel_hi:[1,0,0] neg_lo:[1,0,0] neg_hi:[1,0,0]
	v_pk_mul_f32 v[116:117], v[106:107], v[116:117]
	v_pk_mul_f32 v[108:109], v[110:111], v[108:109]
	v_exp_f32_e32 v116, v116
	v_exp_f32_e32 v108, v108
	v_exp_f32_e32 v109, v109
	v_exp_f32_e32 v117, v117
	v_pk_mul_f32 v[118:119], v[100:101], v[100:101]
	v_pk_add_f32 v[108:109], v[108:109], 1.0 op_sel_hi:[1,0]
	v_pk_add_f32 v[116:117], v[116:117], 1.0 op_sel_hi:[1,0]
	v_pk_fma_f32 v[118:119], v[118:119], s[90:91], v[138:139] op_sel_hi:[1,0,0] neg_lo:[1,0,0] neg_hi:[1,0,0]
	v_rcp_f32_e32 v108, v108
	v_rcp_f32_e32 v109, v109
	v_rcp_f32_e32 v116, v116
	v_rcp_f32_e32 v117, v117
	v_pk_mul_f32 v[118:119], v[100:101], v[118:119]
	v_pk_mul_f32 v[108:109], v[110:111], v[108:109]
	v_exp_f32_e32 v118, v118
	v_exp_f32_e32 v119, v119
	v_pk_mul_f32 v[106:107], v[106:107], v[116:117]
	v_pk_mul_f32 v[110:111], v[96:97], v[96:97]
	v_pk_mul_f32 v[106:107], v[108:109], v[106:107]
	v_pk_add_f32 v[108:109], v[118:119], 1.0 op_sel_hi:[1,0]
	v_pk_fma_f32 v[110:111], v[110:111], 0, s[88:89] op_sel_hi:[1,0,0]
	v_rcp_f32_e32 v108, v108
	v_rcp_f32_e32 v109, v109
	v_pk_mul_f32 v[116:117], v[102:103], v[102:103]
	v_pk_mul_f32 v[110:111], v[96:97], v[110:111]
	v_pk_fma_f32 v[116:117], v[116:117], s[90:91], v[138:139] op_sel_hi:[1,0,0] neg_lo:[1,0,0] neg_hi:[1,0,0]
	v_pk_mul_f32 v[100:101], v[100:101], v[108:109]
	v_pk_mul_f32 v[108:109], v[98:99], v[98:99]
	v_exp_f32_e32 v110, v110
	v_pk_fma_f32 v[108:109], v[108:109], 0, s[88:89] op_sel_hi:[1,0,0]
	v_exp_f32_e32 v111, v111
	v_pk_mul_f32 v[116:117], v[102:103], v[116:117]
	v_pk_mul_f32 v[108:109], v[98:99], v[108:109]
	v_exp_f32_e32 v116, v116
	v_exp_f32_e32 v117, v117
	v_exp_f32_e32 v108, v108
	v_exp_f32_e32 v109, v109
	v_pk_add_f32 v[110:111], v[110:111], 1.0 op_sel_hi:[1,0]
	v_pk_add_f32 v[116:117], v[116:117], 1.0 op_sel_hi:[1,0]
	v_rcp_f32_e32 v110, v110
	v_rcp_f32_e32 v111, v111
	v_pk_add_f32 v[108:109], v[108:109], 1.0 op_sel_hi:[1,0]
	v_rcp_f32_e32 v116, v116
	v_rcp_f32_e32 v117, v117
	v_rcp_f32_e32 v108, v108
	v_rcp_f32_e32 v109, v109
	v_pk_mul_f32 v[96:97], v[96:97], v[110:111]
	v_pk_mul_f32 v[98:99], v[98:99], v[108:109]
	v_pk_mul_f32 v[100:101], v[100:101], v[96:97]
	v_pk_mul_f32 v[96:97], v[102:103], v[116:117]
	s_nop 0
	v_pk_mul_f32 v[102:103], v[96:97], v[98:99]
	v_cvt_pk_bf16_f32 v98, v100, v101
	v_or_b32_e32 v100, 16, v136
	v_ashrrev_i32_e32 v101, 31, v100
	v_lshlrev_b64 v[100:101], 12, v[100:101]
	v_lshl_add_u64 v[100:101], s[58:59], 0, v[100:101]
	v_cvt_pk_bf16_f32 v96, v104, v105
	v_cvt_pk_bf16_f32 v97, v106, v107
	v_cvt_pk_bf16_f32 v99, v102, v103
	v_lshl_add_u64 v[100:101], v[100:101], 0, v[114:115]
	global_store_dwordx4 v[100:101], v[96:99], off sc1
	v_pk_mul_f32 v[100:101], v[94:95], v[94:95]
	s_nop 0
	v_pk_mul_f32 v[96:97], v[92:93], v[92:93]
	v_pk_mul_f32 v[98:99], v[88:89], v[88:89]
	v_pk_fma_f32 v[96:97], v[96:97], s[90:91], v[138:139] op_sel_hi:[1,0,0] neg_lo:[1,0,0] neg_hi:[1,0,0]
	v_pk_fma_f32 v[98:99], v[98:99], 0, s[88:89] op_sel_hi:[1,0,0]
	v_pk_mul_f32 v[96:97], v[92:93], v[96:97]
	v_pk_mul_f32 v[98:99], v[88:89], v[98:99]
	v_exp_f32_e32 v96, v96
	v_exp_f32_e32 v97, v97
	v_exp_f32_e32 v98, v98
	v_exp_f32_e32 v99, v99
	v_pk_add_f32 v[96:97], v[96:97], 1.0 op_sel_hi:[1,0]
	s_nop 0
	v_rcp_f32_e32 v96, v96
	v_pk_add_f32 v[98:99], v[98:99], 1.0 op_sel_hi:[1,0]
	v_rcp_f32_e32 v97, v97
	v_rcp_f32_e32 v98, v98
	v_rcp_f32_e32 v99, v99
	v_pk_mul_f32 v[92:93], v[92:93], v[96:97]
	v_pk_mul_f32 v[96:97], v[90:91], v[90:91]
	v_pk_mul_f32 v[88:89], v[88:89], v[98:99]
	v_pk_fma_f32 v[96:97], v[96:97], 0, s[88:89] op_sel_hi:[1,0,0]
	v_pk_mul_f32 v[88:89], v[92:93], v[88:89]
	v_pk_fma_f32 v[92:93], v[100:101], s[90:91], v[138:139] op_sel_hi:[1,0,0] neg_lo:[1,0,0] neg_hi:[1,0,0]
	v_pk_mul_f32 v[96:97], v[90:91], v[96:97]
	v_pk_mul_f32 v[92:93], v[94:95], v[92:93]
	v_exp_f32_e32 v96, v96
	v_exp_f32_e32 v92, v92
	v_exp_f32_e32 v93, v93
	v_exp_f32_e32 v97, v97
	v_pk_mul_f32 v[98:99], v[84:85], v[84:85]
	v_pk_add_f32 v[92:93], v[92:93], 1.0 op_sel_hi:[1,0]
	v_pk_add_f32 v[96:97], v[96:97], 1.0 op_sel_hi:[1,0]
	v_pk_fma_f32 v[98:99], v[98:99], s[90:91], v[138:139] op_sel_hi:[1,0,0] neg_lo:[1,0,0] neg_hi:[1,0,0]
	v_rcp_f32_e32 v92, v92
	v_rcp_f32_e32 v93, v93
	v_rcp_f32_e32 v96, v96
	v_rcp_f32_e32 v97, v97
	v_pk_mul_f32 v[98:99], v[84:85], v[98:99]
	v_pk_mul_f32 v[92:93], v[94:95], v[92:93]
	v_exp_f32_e32 v98, v98
	v_exp_f32_e32 v99, v99
	v_pk_mul_f32 v[90:91], v[90:91], v[96:97]
	v_pk_mul_f32 v[94:95], v[80:81], v[80:81]
	v_pk_mul_f32 v[90:91], v[92:93], v[90:91]
	v_pk_add_f32 v[92:93], v[98:99], 1.0 op_sel_hi:[1,0]
	v_pk_fma_f32 v[94:95], v[94:95], 0, s[88:89] op_sel_hi:[1,0,0]
	v_rcp_f32_e32 v92, v92
	v_rcp_f32_e32 v93, v93
	v_pk_mul_f32 v[96:97], v[86:87], v[86:87]
	v_pk_mul_f32 v[94:95], v[80:81], v[94:95]
	v_pk_fma_f32 v[96:97], v[96:97], s[90:91], v[138:139] op_sel_hi:[1,0,0] neg_lo:[1,0,0] neg_hi:[1,0,0]
	v_pk_mul_f32 v[84:85], v[84:85], v[92:93]
	v_pk_mul_f32 v[92:93], v[82:83], v[82:83]
	v_exp_f32_e32 v94, v94
	v_pk_fma_f32 v[92:93], v[92:93], 0, s[88:89] op_sel_hi:[1,0,0]
	v_exp_f32_e32 v95, v95
	v_pk_mul_f32 v[96:97], v[86:87], v[96:97]
	v_pk_mul_f32 v[92:93], v[82:83], v[92:93]
	v_exp_f32_e32 v96, v96
	v_exp_f32_e32 v97, v97
	v_exp_f32_e32 v92, v92
	v_exp_f32_e32 v93, v93
	v_pk_add_f32 v[94:95], v[94:95], 1.0 op_sel_hi:[1,0]
	v_pk_add_f32 v[96:97], v[96:97], 1.0 op_sel_hi:[1,0]
	v_rcp_f32_e32 v94, v94
	v_rcp_f32_e32 v95, v95
	v_pk_add_f32 v[92:93], v[92:93], 1.0 op_sel_hi:[1,0]
	v_rcp_f32_e32 v96, v96
	v_rcp_f32_e32 v97, v97
	v_rcp_f32_e32 v92, v92
	v_rcp_f32_e32 v93, v93
	v_pk_mul_f32 v[80:81], v[80:81], v[94:95]
	v_pk_mul_f32 v[82:83], v[82:83], v[92:93]
	v_pk_mul_f32 v[84:85], v[84:85], v[80:81]
	v_pk_mul_f32 v[80:81], v[86:87], v[96:97]
	s_nop 0
	v_pk_mul_f32 v[86:87], v[80:81], v[82:83]
	v_cvt_pk_bf16_f32 v82, v84, v85
	v_or_b32_e32 v84, 32, v136
	v_ashrrev_i32_e32 v85, 31, v84
	v_lshlrev_b64 v[84:85], 12, v[84:85]
	v_lshl_add_u64 v[84:85], s[58:59], 0, v[84:85]
	v_cvt_pk_bf16_f32 v80, v88, v89
	v_cvt_pk_bf16_f32 v81, v90, v91
	v_cvt_pk_bf16_f32 v83, v86, v87
	v_lshl_add_u64 v[84:85], v[84:85], 0, v[114:115]
	global_store_dwordx4 v[84:85], v[80:83], off sc1
	v_pk_mul_f32 v[84:85], v[78:79], v[78:79]
	s_nop 0
	v_pk_mul_f32 v[80:81], v[76:77], v[76:77]
	v_pk_mul_f32 v[82:83], v[72:73], v[72:73]
	v_pk_fma_f32 v[80:81], v[80:81], s[90:91], v[138:139] op_sel_hi:[1,0,0] neg_lo:[1,0,0] neg_hi:[1,0,0]
	v_pk_fma_f32 v[82:83], v[82:83], 0, s[88:89] op_sel_hi:[1,0,0]
	v_pk_mul_f32 v[80:81], v[76:77], v[80:81]
	v_pk_mul_f32 v[82:83], v[72:73], v[82:83]
	v_exp_f32_e32 v80, v80
	v_exp_f32_e32 v81, v81
	v_exp_f32_e32 v82, v82
	v_exp_f32_e32 v83, v83
	v_pk_add_f32 v[80:81], v[80:81], 1.0 op_sel_hi:[1,0]
	s_nop 0
	v_rcp_f32_e32 v80, v80
	v_pk_add_f32 v[82:83], v[82:83], 1.0 op_sel_hi:[1,0]
	v_rcp_f32_e32 v81, v81
	v_rcp_f32_e32 v82, v82
	v_rcp_f32_e32 v83, v83
	v_pk_mul_f32 v[76:77], v[76:77], v[80:81]
	v_pk_mul_f32 v[80:81], v[74:75], v[74:75]
	v_pk_mul_f32 v[72:73], v[72:73], v[82:83]
	v_pk_fma_f32 v[80:81], v[80:81], 0, s[88:89] op_sel_hi:[1,0,0]
	v_pk_mul_f32 v[72:73], v[76:77], v[72:73]
	v_pk_fma_f32 v[76:77], v[84:85], s[90:91], v[138:139] op_sel_hi:[1,0,0] neg_lo:[1,0,0] neg_hi:[1,0,0]
	v_pk_mul_f32 v[80:81], v[74:75], v[80:81]
	v_pk_mul_f32 v[76:77], v[78:79], v[76:77]
	v_exp_f32_e32 v80, v80
	v_exp_f32_e32 v76, v76
	v_exp_f32_e32 v77, v77
	v_exp_f32_e32 v81, v81
	v_pk_mul_f32 v[82:83], v[68:69], v[68:69]
	v_pk_add_f32 v[76:77], v[76:77], 1.0 op_sel_hi:[1,0]
	v_pk_add_f32 v[80:81], v[80:81], 1.0 op_sel_hi:[1,0]
	v_pk_fma_f32 v[82:83], v[82:83], s[90:91], v[138:139] op_sel_hi:[1,0,0] neg_lo:[1,0,0] neg_hi:[1,0,0]
	v_rcp_f32_e32 v76, v76
	v_rcp_f32_e32 v77, v77
	v_rcp_f32_e32 v80, v80
	v_rcp_f32_e32 v81, v81
	v_pk_mul_f32 v[82:83], v[68:69], v[82:83]
	v_pk_mul_f32 v[76:77], v[78:79], v[76:77]
	v_exp_f32_e32 v82, v82
	v_exp_f32_e32 v83, v83
	v_pk_mul_f32 v[74:75], v[74:75], v[80:81]
	v_pk_mul_f32 v[78:79], v[64:65], v[64:65]
	v_pk_mul_f32 v[74:75], v[76:77], v[74:75]
	v_pk_add_f32 v[76:77], v[82:83], 1.0 op_sel_hi:[1,0]
	v_pk_fma_f32 v[78:79], v[78:79], 0, s[88:89] op_sel_hi:[1,0,0]
	v_rcp_f32_e32 v76, v76
	v_rcp_f32_e32 v77, v77
	v_pk_mul_f32 v[80:81], v[70:71], v[70:71]
	v_pk_mul_f32 v[78:79], v[64:65], v[78:79]
	v_pk_fma_f32 v[80:81], v[80:81], s[90:91], v[138:139] op_sel_hi:[1,0,0] neg_lo:[1,0,0] neg_hi:[1,0,0]
	v_pk_mul_f32 v[68:69], v[68:69], v[76:77]
	v_pk_mul_f32 v[76:77], v[66:67], v[66:67]
	v_exp_f32_e32 v78, v78
	v_pk_fma_f32 v[76:77], v[76:77], 0, s[88:89] op_sel_hi:[1,0,0]
	v_exp_f32_e32 v79, v79
	v_pk_mul_f32 v[80:81], v[70:71], v[80:81]
	v_pk_mul_f32 v[76:77], v[66:67], v[76:77]
	v_exp_f32_e32 v80, v80
	v_exp_f32_e32 v81, v81
	v_exp_f32_e32 v76, v76
	v_exp_f32_e32 v77, v77
	v_pk_add_f32 v[78:79], v[78:79], 1.0 op_sel_hi:[1,0]
	v_pk_add_f32 v[80:81], v[80:81], 1.0 op_sel_hi:[1,0]
	v_rcp_f32_e32 v78, v78
	v_rcp_f32_e32 v79, v79
	v_pk_add_f32 v[76:77], v[76:77], 1.0 op_sel_hi:[1,0]
	v_rcp_f32_e32 v80, v80
	v_rcp_f32_e32 v81, v81
	v_rcp_f32_e32 v76, v76
	v_rcp_f32_e32 v77, v77
	v_pk_mul_f32 v[64:65], v[64:65], v[78:79]
	v_pk_mul_f32 v[66:67], v[66:67], v[76:77]
	v_pk_mul_f32 v[68:69], v[68:69], v[64:65]
	v_pk_mul_f32 v[64:65], v[70:71], v[80:81]
	s_nop 0
	v_pk_mul_f32 v[70:71], v[64:65], v[66:67]
	v_cvt_pk_bf16_f32 v66, v68, v69
	v_or_b32_e32 v68, 48, v136
	v_ashrrev_i32_e32 v69, 31, v68
	v_lshlrev_b64 v[68:69], 12, v[68:69]
	v_lshl_add_u64 v[68:69], s[58:59], 0, v[68:69]
	v_cvt_pk_bf16_f32 v64, v72, v73
	v_cvt_pk_bf16_f32 v65, v74, v75
	v_cvt_pk_bf16_f32 v67, v70, v71
	v_lshl_add_u64 v[68:69], v[68:69], 0, v[114:115]
	global_store_dwordx4 v[68:69], v[64:67], off sc1
	v_pk_mul_f32 v[68:69], v[62:63], v[62:63]
	s_nop 0
	v_pk_mul_f32 v[64:65], v[60:61], v[60:61]
	v_pk_mul_f32 v[66:67], v[56:57], v[56:57]
	v_pk_fma_f32 v[64:65], v[64:65], s[90:91], v[138:139] op_sel_hi:[1,0,0] neg_lo:[1,0,0] neg_hi:[1,0,0]
	v_pk_fma_f32 v[66:67], v[66:67], 0, s[88:89] op_sel_hi:[1,0,0]
	v_pk_mul_f32 v[64:65], v[60:61], v[64:65]
	v_pk_mul_f32 v[66:67], v[56:57], v[66:67]
	v_exp_f32_e32 v64, v64
	v_exp_f32_e32 v65, v65
	v_exp_f32_e32 v66, v66
	v_exp_f32_e32 v67, v67
	v_pk_add_f32 v[64:65], v[64:65], 1.0 op_sel_hi:[1,0]
	s_nop 0
	v_rcp_f32_e32 v64, v64
	v_pk_add_f32 v[66:67], v[66:67], 1.0 op_sel_hi:[1,0]
	v_rcp_f32_e32 v65, v65
	v_rcp_f32_e32 v66, v66
	v_rcp_f32_e32 v67, v67
	v_pk_mul_f32 v[60:61], v[60:61], v[64:65]
	v_pk_mul_f32 v[64:65], v[58:59], v[58:59]
	v_pk_mul_f32 v[56:57], v[56:57], v[66:67]
	v_pk_fma_f32 v[64:65], v[64:65], 0, s[88:89] op_sel_hi:[1,0,0]
	v_pk_mul_f32 v[56:57], v[60:61], v[56:57]
	v_pk_fma_f32 v[60:61], v[68:69], s[90:91], v[138:139] op_sel_hi:[1,0,0] neg_lo:[1,0,0] neg_hi:[1,0,0]
	v_pk_mul_f32 v[64:65], v[58:59], v[64:65]
	v_pk_mul_f32 v[60:61], v[62:63], v[60:61]
	v_exp_f32_e32 v64, v64
	v_exp_f32_e32 v60, v60
	v_exp_f32_e32 v61, v61
	v_exp_f32_e32 v65, v65
	v_pk_mul_f32 v[66:67], v[52:53], v[52:53]
	v_pk_add_f32 v[60:61], v[60:61], 1.0 op_sel_hi:[1,0]
	v_pk_add_f32 v[64:65], v[64:65], 1.0 op_sel_hi:[1,0]
	v_pk_fma_f32 v[66:67], v[66:67], s[90:91], v[138:139] op_sel_hi:[1,0,0] neg_lo:[1,0,0] neg_hi:[1,0,0]
	v_rcp_f32_e32 v60, v60
	v_rcp_f32_e32 v61, v61
	v_rcp_f32_e32 v64, v64
	v_rcp_f32_e32 v65, v65
	v_pk_mul_f32 v[66:67], v[52:53], v[66:67]
	v_pk_mul_f32 v[60:61], v[62:63], v[60:61]
	v_exp_f32_e32 v66, v66
	v_exp_f32_e32 v67, v67
	v_pk_mul_f32 v[58:59], v[58:59], v[64:65]
	v_pk_mul_f32 v[62:63], v[48:49], v[48:49]
	v_pk_mul_f32 v[58:59], v[60:61], v[58:59]
	v_pk_add_f32 v[60:61], v[66:67], 1.0 op_sel_hi:[1,0]
	v_pk_fma_f32 v[62:63], v[62:63], 0, s[88:89] op_sel_hi:[1,0,0]
	v_rcp_f32_e32 v60, v60
	v_rcp_f32_e32 v61, v61
	v_pk_mul_f32 v[64:65], v[54:55], v[54:55]
	v_pk_mul_f32 v[62:63], v[48:49], v[62:63]
	v_pk_fma_f32 v[64:65], v[64:65], s[90:91], v[138:139] op_sel_hi:[1,0,0] neg_lo:[1,0,0] neg_hi:[1,0,0]
	v_pk_mul_f32 v[52:53], v[52:53], v[60:61]
	v_pk_mul_f32 v[60:61], v[50:51], v[50:51]
	v_exp_f32_e32 v62, v62
	v_pk_fma_f32 v[60:61], v[60:61], 0, s[88:89] op_sel_hi:[1,0,0]
	v_exp_f32_e32 v63, v63
	v_pk_mul_f32 v[64:65], v[54:55], v[64:65]
	v_pk_mul_f32 v[60:61], v[50:51], v[60:61]
	v_exp_f32_e32 v64, v64
	v_exp_f32_e32 v65, v65
	v_exp_f32_e32 v60, v60
	v_exp_f32_e32 v61, v61
	v_pk_add_f32 v[62:63], v[62:63], 1.0 op_sel_hi:[1,0]
	v_pk_add_f32 v[64:65], v[64:65], 1.0 op_sel_hi:[1,0]
	v_rcp_f32_e32 v62, v62
	v_rcp_f32_e32 v63, v63
	v_pk_add_f32 v[60:61], v[60:61], 1.0 op_sel_hi:[1,0]
	v_rcp_f32_e32 v64, v64
	v_rcp_f32_e32 v65, v65
	v_rcp_f32_e32 v60, v60
	v_rcp_f32_e32 v61, v61
	v_pk_mul_f32 v[48:49], v[48:49], v[62:63]
	v_pk_mul_f32 v[50:51], v[50:51], v[60:61]
	v_pk_mul_f32 v[52:53], v[52:53], v[48:49]
	v_pk_mul_f32 v[48:49], v[54:55], v[64:65]
	s_nop 0
	v_pk_mul_f32 v[54:55], v[48:49], v[50:51]
	v_cvt_pk_bf16_f32 v50, v52, v53
	v_add_co_u32_e32 v52, vcc, s3, v112
	v_cvt_pk_bf16_f32 v48, v56, v57
	v_cvt_pk_bf16_f32 v49, v58, v59
	v_cvt_pk_bf16_f32 v51, v54, v55
	s_mov_b32 s3, 0x90000
	s_nop 0
	v_addc_co_u32_e32 v53, vcc, 0, v113, vcc
	global_store_dwordx4 v[52:53], v[48:51], off sc1
	v_pk_mul_f32 v[52:53], v[46:47], v[46:47]
	s_nop 0
	v_pk_mul_f32 v[48:49], v[44:45], v[44:45]
	v_pk_mul_f32 v[50:51], v[40:41], v[40:41]
	v_pk_fma_f32 v[48:49], v[48:49], s[90:91], v[138:139] op_sel_hi:[1,0,0] neg_lo:[1,0,0] neg_hi:[1,0,0]
	v_pk_fma_f32 v[50:51], v[50:51], 0, s[88:89] op_sel_hi:[1,0,0]
	v_pk_mul_f32 v[48:49], v[44:45], v[48:49]
	v_pk_mul_f32 v[50:51], v[40:41], v[50:51]
	v_exp_f32_e32 v48, v48
	v_exp_f32_e32 v49, v49
	v_exp_f32_e32 v50, v50
	v_exp_f32_e32 v51, v51
	v_pk_add_f32 v[48:49], v[48:49], 1.0 op_sel_hi:[1,0]
	s_nop 0
	v_rcp_f32_e32 v48, v48
	v_pk_add_f32 v[50:51], v[50:51], 1.0 op_sel_hi:[1,0]
	v_rcp_f32_e32 v49, v49
	v_rcp_f32_e32 v50, v50
	v_rcp_f32_e32 v51, v51
	v_pk_mul_f32 v[44:45], v[44:45], v[48:49]
	v_pk_mul_f32 v[48:49], v[42:43], v[42:43]
	v_pk_mul_f32 v[40:41], v[40:41], v[50:51]
	v_pk_fma_f32 v[48:49], v[48:49], 0, s[88:89] op_sel_hi:[1,0,0]
	v_pk_mul_f32 v[40:41], v[44:45], v[40:41]
	v_pk_fma_f32 v[44:45], v[52:53], s[90:91], v[138:139] op_sel_hi:[1,0,0] neg_lo:[1,0,0] neg_hi:[1,0,0]
	v_pk_mul_f32 v[48:49], v[42:43], v[48:49]
	v_pk_mul_f32 v[44:45], v[46:47], v[44:45]
	v_exp_f32_e32 v48, v48
	v_exp_f32_e32 v44, v44
	v_exp_f32_e32 v45, v45
	v_exp_f32_e32 v49, v49
	v_pk_mul_f32 v[50:51], v[36:37], v[36:37]
	v_pk_add_f32 v[44:45], v[44:45], 1.0 op_sel_hi:[1,0]
	v_pk_add_f32 v[48:49], v[48:49], 1.0 op_sel_hi:[1,0]
	v_pk_fma_f32 v[50:51], v[50:51], s[90:91], v[138:139] op_sel_hi:[1,0,0] neg_lo:[1,0,0] neg_hi:[1,0,0]
	v_rcp_f32_e32 v44, v44
	v_rcp_f32_e32 v45, v45
	v_rcp_f32_e32 v48, v48
	v_rcp_f32_e32 v49, v49
	v_pk_mul_f32 v[50:51], v[36:37], v[50:51]
	v_pk_mul_f32 v[44:45], v[46:47], v[44:45]
	v_exp_f32_e32 v50, v50
	v_exp_f32_e32 v51, v51
	v_pk_mul_f32 v[42:43], v[42:43], v[48:49]
	v_pk_mul_f32 v[46:47], v[32:33], v[32:33]
	v_pk_mul_f32 v[42:43], v[44:45], v[42:43]
	v_pk_add_f32 v[44:45], v[50:51], 1.0 op_sel_hi:[1,0]
	v_pk_fma_f32 v[46:47], v[46:47], 0, s[88:89] op_sel_hi:[1,0,0]
	v_rcp_f32_e32 v44, v44
	v_rcp_f32_e32 v45, v45
	v_pk_mul_f32 v[48:49], v[38:39], v[38:39]
	v_pk_mul_f32 v[46:47], v[32:33], v[46:47]
	v_pk_fma_f32 v[48:49], v[48:49], s[90:91], v[138:139] op_sel_hi:[1,0,0] neg_lo:[1,0,0] neg_hi:[1,0,0]
	v_pk_mul_f32 v[36:37], v[36:37], v[44:45]
	v_pk_mul_f32 v[44:45], v[34:35], v[34:35]
	v_exp_f32_e32 v46, v46
	v_pk_fma_f32 v[44:45], v[44:45], 0, s[88:89] op_sel_hi:[1,0,0]
	v_exp_f32_e32 v47, v47
	v_pk_mul_f32 v[48:49], v[38:39], v[48:49]
	v_pk_mul_f32 v[44:45], v[34:35], v[44:45]
	v_exp_f32_e32 v48, v48
	v_exp_f32_e32 v49, v49
	v_exp_f32_e32 v44, v44
	v_exp_f32_e32 v45, v45
	v_pk_add_f32 v[46:47], v[46:47], 1.0 op_sel_hi:[1,0]
	v_pk_add_f32 v[48:49], v[48:49], 1.0 op_sel_hi:[1,0]
	v_rcp_f32_e32 v46, v46
	v_rcp_f32_e32 v47, v47
	v_pk_add_f32 v[44:45], v[44:45], 1.0 op_sel_hi:[1,0]
	v_rcp_f32_e32 v48, v48
	v_rcp_f32_e32 v49, v49
	v_rcp_f32_e32 v44, v44
	v_rcp_f32_e32 v45, v45
	v_pk_mul_f32 v[32:33], v[32:33], v[46:47]
	v_pk_mul_f32 v[34:35], v[34:35], v[44:45]
	v_pk_mul_f32 v[36:37], v[36:37], v[32:33]
	v_pk_mul_f32 v[32:33], v[38:39], v[48:49]
	s_nop 0
	v_pk_mul_f32 v[38:39], v[32:33], v[34:35]
	v_cvt_pk_bf16_f32 v34, v36, v37
	v_add_co_u32_e32 v36, vcc, s3, v112
	v_cvt_pk_bf16_f32 v32, v40, v41
	v_cvt_pk_bf16_f32 v33, v42, v43
	v_cvt_pk_bf16_f32 v35, v38, v39
	s_mov_b32 s3, 0xa0000
	s_nop 0
	v_addc_co_u32_e32 v37, vcc, 0, v113, vcc
	global_store_dwordx4 v[36:37], v[32:35], off sc1
	v_pk_mul_f32 v[36:37], v[30:31], v[30:31]
	s_nop 0
	v_pk_mul_f32 v[32:33], v[28:29], v[28:29]
	v_pk_mul_f32 v[34:35], v[24:25], v[24:25]
	v_pk_fma_f32 v[32:33], v[32:33], s[90:91], v[138:139] op_sel_hi:[1,0,0] neg_lo:[1,0,0] neg_hi:[1,0,0]
	v_pk_fma_f32 v[34:35], v[34:35], 0, s[88:89] op_sel_hi:[1,0,0]
	v_pk_mul_f32 v[32:33], v[28:29], v[32:33]
	v_pk_mul_f32 v[34:35], v[24:25], v[34:35]
	v_exp_f32_e32 v32, v32
	v_exp_f32_e32 v33, v33
	v_exp_f32_e32 v34, v34
	v_exp_f32_e32 v35, v35
	v_pk_add_f32 v[32:33], v[32:33], 1.0 op_sel_hi:[1,0]
	s_nop 0
	v_rcp_f32_e32 v32, v32
	v_pk_add_f32 v[34:35], v[34:35], 1.0 op_sel_hi:[1,0]
	v_rcp_f32_e32 v33, v33
	v_rcp_f32_e32 v34, v34
	v_rcp_f32_e32 v35, v35
	v_pk_mul_f32 v[28:29], v[28:29], v[32:33]
	v_pk_mul_f32 v[32:33], v[26:27], v[26:27]
	v_pk_mul_f32 v[24:25], v[24:25], v[34:35]
	v_pk_fma_f32 v[32:33], v[32:33], 0, s[88:89] op_sel_hi:[1,0,0]
	v_pk_mul_f32 v[24:25], v[28:29], v[24:25]
	v_pk_fma_f32 v[28:29], v[36:37], s[90:91], v[138:139] op_sel_hi:[1,0,0] neg_lo:[1,0,0] neg_hi:[1,0,0]
	v_pk_mul_f32 v[32:33], v[26:27], v[32:33]
	v_pk_mul_f32 v[28:29], v[30:31], v[28:29]
	v_exp_f32_e32 v32, v32
	v_exp_f32_e32 v28, v28
	v_exp_f32_e32 v29, v29
	v_exp_f32_e32 v33, v33
	v_pk_mul_f32 v[34:35], v[20:21], v[20:21]
	v_pk_add_f32 v[28:29], v[28:29], 1.0 op_sel_hi:[1,0]
	v_pk_add_f32 v[32:33], v[32:33], 1.0 op_sel_hi:[1,0]
	v_pk_fma_f32 v[34:35], v[34:35], s[90:91], v[138:139] op_sel_hi:[1,0,0] neg_lo:[1,0,0] neg_hi:[1,0,0]
	v_rcp_f32_e32 v28, v28
	v_rcp_f32_e32 v29, v29
	v_rcp_f32_e32 v32, v32
	v_rcp_f32_e32 v33, v33
	v_pk_mul_f32 v[34:35], v[20:21], v[34:35]
	v_pk_mul_f32 v[28:29], v[30:31], v[28:29]
	v_exp_f32_e32 v34, v34
	v_exp_f32_e32 v35, v35
	v_pk_mul_f32 v[26:27], v[26:27], v[32:33]
	v_pk_mul_f32 v[30:31], v[16:17], v[16:17]
	v_pk_mul_f32 v[26:27], v[28:29], v[26:27]
	v_pk_add_f32 v[28:29], v[34:35], 1.0 op_sel_hi:[1,0]
	v_pk_fma_f32 v[30:31], v[30:31], 0, s[88:89] op_sel_hi:[1,0,0]
	v_rcp_f32_e32 v28, v28
	v_rcp_f32_e32 v29, v29
	v_pk_mul_f32 v[32:33], v[22:23], v[22:23]
	v_pk_mul_f32 v[30:31], v[16:17], v[30:31]
	v_pk_fma_f32 v[32:33], v[32:33], s[90:91], v[138:139] op_sel_hi:[1,0,0] neg_lo:[1,0,0] neg_hi:[1,0,0]
	v_pk_mul_f32 v[20:21], v[20:21], v[28:29]
	v_pk_mul_f32 v[28:29], v[18:19], v[18:19]
	v_exp_f32_e32 v30, v30
	v_pk_fma_f32 v[28:29], v[28:29], 0, s[88:89] op_sel_hi:[1,0,0]
	v_exp_f32_e32 v31, v31
	v_pk_mul_f32 v[32:33], v[22:23], v[32:33]
	v_pk_mul_f32 v[28:29], v[18:19], v[28:29]
	v_exp_f32_e32 v32, v32
	v_exp_f32_e32 v33, v33
	v_exp_f32_e32 v28, v28
	v_exp_f32_e32 v29, v29
	v_pk_add_f32 v[30:31], v[30:31], 1.0 op_sel_hi:[1,0]
	v_pk_add_f32 v[32:33], v[32:33], 1.0 op_sel_hi:[1,0]
	v_rcp_f32_e32 v30, v30
	v_rcp_f32_e32 v31, v31
	v_pk_add_f32 v[28:29], v[28:29], 1.0 op_sel_hi:[1,0]
	v_rcp_f32_e32 v32, v32
	v_rcp_f32_e32 v33, v33
	v_rcp_f32_e32 v28, v28
	v_rcp_f32_e32 v29, v29
	v_pk_mul_f32 v[16:17], v[16:17], v[30:31]
	v_pk_mul_f32 v[18:19], v[18:19], v[28:29]
	v_pk_mul_f32 v[20:21], v[20:21], v[16:17]
	v_pk_mul_f32 v[16:17], v[22:23], v[32:33]
	s_nop 0
	v_pk_mul_f32 v[22:23], v[16:17], v[18:19]
	v_cvt_pk_bf16_f32 v18, v20, v21
	v_add_co_u32_e32 v20, vcc, s3, v112
	v_cvt_pk_bf16_f32 v16, v24, v25
	v_cvt_pk_bf16_f32 v17, v26, v27
	v_cvt_pk_bf16_f32 v19, v22, v23
	s_nop 1
	v_addc_co_u32_e32 v21, vcc, 0, v113, vcc
	global_store_dwordx4 v[20:21], v[16:19], off sc1
	v_pk_mul_f32 v[20:21], v[14:15], v[14:15]
	s_nop 0
	v_pk_mul_f32 v[16:17], v[12:13], v[12:13]
	v_pk_mul_f32 v[18:19], v[8:9], v[8:9]
	v_pk_fma_f32 v[16:17], v[16:17], s[90:91], v[138:139] op_sel_hi:[1,0,0] neg_lo:[1,0,0] neg_hi:[1,0,0]
	v_pk_fma_f32 v[18:19], v[18:19], 0, s[88:89] op_sel_hi:[1,0,0]
	v_pk_mul_f32 v[16:17], v[12:13], v[16:17]
	v_pk_mul_f32 v[18:19], v[8:9], v[18:19]
	v_exp_f32_e32 v16, v16
	v_exp_f32_e32 v17, v17
	v_exp_f32_e32 v18, v18
	v_exp_f32_e32 v19, v19
	v_pk_add_f32 v[16:17], v[16:17], 1.0 op_sel_hi:[1,0]
	s_nop 0
	v_rcp_f32_e32 v16, v16
	v_pk_add_f32 v[18:19], v[18:19], 1.0 op_sel_hi:[1,0]
	v_rcp_f32_e32 v17, v17
	v_rcp_f32_e32 v18, v18
	v_rcp_f32_e32 v19, v19
	v_pk_mul_f32 v[12:13], v[12:13], v[16:17]
	v_pk_mul_f32 v[16:17], v[10:11], v[10:11]
	v_pk_mul_f32 v[8:9], v[8:9], v[18:19]
	v_pk_fma_f32 v[16:17], v[16:17], 0, s[88:89] op_sel_hi:[1,0,0]
	v_pk_mul_f32 v[8:9], v[12:13], v[8:9]
	v_pk_fma_f32 v[12:13], v[20:21], s[90:91], v[138:139] op_sel_hi:[1,0,0] neg_lo:[1,0,0] neg_hi:[1,0,0]
	v_pk_mul_f32 v[16:17], v[10:11], v[16:17]
	v_pk_mul_f32 v[12:13], v[14:15], v[12:13]
	v_exp_f32_e32 v16, v16
	v_exp_f32_e32 v12, v12
	v_exp_f32_e32 v13, v13
	v_exp_f32_e32 v17, v17
	v_pk_mul_f32 v[18:19], v[4:5], v[4:5]
	v_pk_add_f32 v[12:13], v[12:13], 1.0 op_sel_hi:[1,0]
	v_pk_add_f32 v[16:17], v[16:17], 1.0 op_sel_hi:[1,0]
	v_pk_fma_f32 v[18:19], v[18:19], s[90:91], v[138:139] op_sel_hi:[1,0,0] neg_lo:[1,0,0] neg_hi:[1,0,0]
	v_rcp_f32_e32 v12, v12
	v_rcp_f32_e32 v13, v13
	v_rcp_f32_e32 v16, v16
	v_rcp_f32_e32 v17, v17
	v_pk_mul_f32 v[18:19], v[4:5], v[18:19]
	v_pk_mul_f32 v[12:13], v[14:15], v[12:13]
	v_exp_f32_e32 v18, v18
	v_exp_f32_e32 v19, v19
	v_pk_mul_f32 v[10:11], v[10:11], v[16:17]
	v_pk_mul_f32 v[14:15], v[0:1], v[0:1]
	v_pk_mul_f32 v[10:11], v[12:13], v[10:11]
	v_pk_add_f32 v[12:13], v[18:19], 1.0 op_sel_hi:[1,0]
	v_pk_fma_f32 v[14:15], v[14:15], 0, s[88:89] op_sel_hi:[1,0,0]
	v_rcp_f32_e32 v12, v12
	v_rcp_f32_e32 v13, v13
	v_pk_mul_f32 v[16:17], v[6:7], v[6:7]
	v_pk_mul_f32 v[14:15], v[0:1], v[14:15]
	v_pk_fma_f32 v[16:17], v[16:17], s[90:91], v[138:139] op_sel_hi:[1,0,0] neg_lo:[1,0,0] neg_hi:[1,0,0]
	v_pk_mul_f32 v[4:5], v[4:5], v[12:13]
	v_pk_mul_f32 v[12:13], v[2:3], v[2:3]
	v_exp_f32_e32 v14, v14
	v_pk_fma_f32 v[12:13], v[12:13], 0, s[88:89] op_sel_hi:[1,0,0]
	v_exp_f32_e32 v15, v15
	v_pk_mul_f32 v[16:17], v[6:7], v[16:17]
	v_pk_mul_f32 v[12:13], v[2:3], v[12:13]
	v_exp_f32_e32 v16, v16
	v_exp_f32_e32 v17, v17
	v_exp_f32_e32 v12, v12
	v_exp_f32_e32 v13, v13
	v_pk_add_f32 v[14:15], v[14:15], 1.0 op_sel_hi:[1,0]
	v_pk_add_f32 v[16:17], v[16:17], 1.0 op_sel_hi:[1,0]
	v_rcp_f32_e32 v14, v14
	v_rcp_f32_e32 v15, v15
	v_pk_add_f32 v[12:13], v[12:13], 1.0 op_sel_hi:[1,0]
	v_rcp_f32_e32 v16, v16
	v_rcp_f32_e32 v17, v17
	v_rcp_f32_e32 v12, v12
	v_rcp_f32_e32 v13, v13
	v_pk_mul_f32 v[0:1], v[0:1], v[14:15]
	v_pk_mul_f32 v[2:3], v[2:3], v[12:13]
	v_pk_mul_f32 v[4:5], v[4:5], v[0:1]
	v_pk_mul_f32 v[0:1], v[6:7], v[16:17]
	s_nop 0
	v_pk_mul_f32 v[6:7], v[0:1], v[2:3]
	v_cvt_pk_bf16_f32 v2, v4, v5
	v_add_co_u32_e32 v4, vcc, 0xb0000, v112
	v_cvt_pk_bf16_f32 v0, v8, v9
	v_cvt_pk_bf16_f32 v1, v10, v11
	v_cvt_pk_bf16_f32 v3, v6, v7
	s_nop 1
	v_addc_co_u32_e32 v5, vcc, 0, v113, vcc
	global_store_dwordx4 v[4:5], v[0:3], off sc1
	s_branch .LBB0_230
